# static s_setprio 1 for blocks >=256 during GEMM phases
# baseline (speedup 1.0000x reference)
.LBB0_70:
	s_setprio 0
	s_cmpk_lt_u32 s2, 0x100
	s_cbranch_scc1 .Lprio_skip_0
	s_setprio 1

.LBB0_164:
	s_setprio 0
	s_bitcmp0_b32 s54, 0
	v_cmp_eq_u32_e64 s[30:31], 0, v147
	v_and_b32_e32 v149, 31, v147
	s_cbranch_scc0 .LBB0_166
	s_bitcmp0_b32 s54, 1
	s_cbranch_scc0 .LBB0_179
	s_branch .LBB0_282

.LBB0_468:
	s_setprio 0
	s_mov_b32 s30, s22
	v_lshlrev_b32_e32 v2, 3, v1
	s_bitcmp0_b32 s22, 0
	s_mov_b32 s17, 0
	s_mov_b64 s[28:29], s[20:21]
	v_cmp_eq_u32_e64 s[52:53], 0, v1
	v_lshrrev_b32_e32 v147, 3, v1
	v_and_b32_e32 v146, 56, v2
	s_cbranch_scc1 .LBB0_530
	s_load_dwordx16 s[60:75], s[0:1], 0x80
	v_mov_b32_e32 v149, 0
	v_lshlrev_b32_e32 v148, 2, v147
	s_movk_i32 s3, 0x80
	v_and_b32_e32 v232, 15, v1
	s_waitcnt lgkmcnt(0)
	v_lshl_add_u64 v[150:151], s[60:61], 0, v[148:149]
	s_load_dwordx16 s[60:75], s[0:1], 0x40
	v_cmp_gt_u32_e64 s[10:11], s3, v1
	v_lshlrev_b32_e32 v3, 1, v146
	s_movk_i32 s3, 0x90
	v_lshlrev_b32_e32 v234, 2, v232
	s_movk_i32 s12, 0x8c
	v_and_b32_e32 v2, 63, v1
	v_lshrrev_b32_e32 v226, 6, v1
	v_and_b32_e32 v227, 3, v1
	v_mad_u32_u24 v231, v147, s3, v3
	v_lshrrev_b32_e32 v233, 4, v1
	v_and_b32_e32 v236, 48, v1
	v_mad_u32_u24 v3, v232, s12, v234
	s_movk_i32 s12, 0xff74
	s_mov_b32 s78, s30
	v_lshrrev_b32_e32 v228, 2, v1
	v_lshl_or_b32 v229, v226, 9, v2
	v_lshlrev_b32_e32 v230, 2, v1
	v_lshlrev_b32_e32 v2, 6, v146
	v_lshlrev_b32_e32 v4, 4, v227
	v_add_u32_e32 v237, v3, v236
	v_mad_i32_i24 v239, v232, s12, v3
	v_mul_u32_u24_e32 v3, 0x44, v233
	s_add_u32 s18, s82, 0xb6c0004
	s_movk_i32 s20, 0xffc0
	s_mov_b64 s[76:77], s[28:29]
	v_cmp_gt_u32_e64 s[4:5], 64, v1
	v_cmp_gt_u32_e64 s[6:7], 16, v1
	v_cmp_lt_u32_e64 s[8:9], 15, v1
	v_lshlrev_b32_e32 v235, 6, v227
	v_and_b32_e32 v238, 12, v228
	v_cmp_eq_u32_e64 s[12:13], 15, v233
	s_movk_i32 s33, 0x44
	v_lshl_add_u32 v240, v3, 2, v239
	s_waitcnt lgkmcnt(0)
	v_lshl_add_u64 v[152:153], s[72:73], 0, v[148:149]
	s_addc_u32 s19, s83, 0
	v_or_b32_e32 v241, 0x4840, v234
	v_mov_b32_e32 v242, 0x11ff0
	s_movk_i32 s36, 0xff
	s_mov_b32 s37, 0x3f2aaaab
	v_mov_b32_e32 v243, 0x3ecc95a3
	s_mov_b32 s38, 0x3f317218
	s_mov_b32 s39, 0x7f800000
	s_mov_b32 s42, 0x33800000
	s_mov_b32 s21, -1
	v_lshlrev_b32_e32 v154, 2, v2
	s_movk_i32 s43, 0x7fff
	v_lshlrev_b32_e32 v156, 2, v4
	s_movk_i32 s44, 0x84
	v_add_u32_e32 v244, 0x2400, v230
	v_mov_b32_e32 v245, 0x7f800000
	v_mov_b32_e32 v246, 0x7fc00000
	v_mov_b32_e32 v247, 0xff800000
	v_mov_b32_e32 v248, 1
	s_branch .LBB0_472
